# stack18 + layer-0 window loop: K tiles loaded two steps ahead into two dedicated register sets (K waits removed)
# baseline (speedup 1.0000x reference)
.LBB0_882:
	v_add_f32_e32 v52, v52, v53
	s_andn2_b64 vcc, exec, s[8:9]
	v_add_f32_e32 v136, v107, v52
	s_cbranch_vccnz .LBB0_846
	s_ashr_i32 s7, s6, 31
	s_ashr_i32 s65, s64, 31
	s_lshl_b64 s[6:7], s[6:7], 1
	s_add_u32 s6, s80, s6
	v_readlane_b32 s10, v254, 40
	s_addc_u32 s7, s81, s7
	s_or_b32 s8, s10, s4
	s_or_b32 s2, s8, s2
	v_add3_u32 v55, v126, s2, 64
	v_mov_b64_e32 v[52:53], s[80:81]
	v_mad_i64_i32 v[52:53], s[8:9], v55, s44, v[52:53]
	v_mov_b32_e32 v51, v1
	v_lshl_add_u64 v[52:53], s[62:63], 1, v[52:53]
	v_lshl_add_u64 v[52:53], v[52:53], 0, v[50:51]
	v_add_co_u32_e32 v56, vcc, s45, v52
	v_sub_u32_e64 v55, v121, 8 clamp
	s_nop 0
	v_addc_co_u32_e32 v57, vcc, 0, v53, vcc
	v_add_co_u32_e32 v58, vcc, s77, v52
	v_min_u32_e32 v55, 48, v55
	s_nop 0
	v_addc_co_u32_e32 v59, vcc, 0, v53, vcc
	v_add_co_u32_e32 v60, vcc, s46, v52
	s_bfe_u32 s2, s68, 0x30003
	s_nop 0
	v_addc_co_u32_e32 v61, vcc, 0, v53, vcc
	global_load_dwordx4 v[224:227], v[58:59], off offset:2048
	global_load_dwordx4 v[220:223], v[60:61], off offset:2048
	global_load_dwordx4 v[228:231], v[56:57], off offset:2048
	global_load_dwordx4 v[216:219], v[52:53], off offset:2048
	v_add_u32_e32 v56, s10, v122
	v_sub_u32_e32 v55, v56, v55
	v_add_u32_e32 v56, 1, v55
	v_cmp_gt_u32_e64 s[8:9], 16, v56
	v_add_u32_e32 v56, 2, v55
	v_cmp_gt_u32_e64 s[10:11], 16, v56
	v_add_u32_e32 v56, 3, v55
	v_cmp_gt_u32_e64 s[12:13], 16, v56
	v_add_u32_e32 v56, 8, v55
	v_cmp_gt_u32_e64 s[14:15], 16, v56
	v_add_u32_e32 v56, 9, v55
	v_cmp_gt_u32_e64 s[16:17], 16, v56
	v_add_u32_e32 v56, 10, v55
	v_cmp_gt_u32_e64 s[18:19], 16, v56
	v_add_u32_e32 v56, 11, v55
	v_cmp_gt_u32_e64 s[20:21], 16, v56
	v_add_u32_e32 v56, 17, v55
	v_lshl_add_u64 v[124:125], s[6:7], 0, v[50:51]
	s_lshl_b32 s6, s2, 2
	v_readlane_b32 s7, v254, 19
	v_cmp_gt_u32_e64 s[24:25], 16, v56
	v_add_u32_e32 v56, 18, v55
	s_add_i32 s33, s7, s6
	v_cmp_gt_u32_e64 s[26:27], 16, v56
	v_add_u32_e32 v56, 19, v55
	v_lshl_add_u64 v[52:53], s[80:81], 0, v[50:51]
	v_sub_u32_e64 v50, s33, 4 clamp
	v_cmp_gt_u32_e64 s[28:29], 16, v56
	v_add_u32_e32 v56, 24, v55
	v_min_u32_e32 v50, 24, v50
	s_movk_i32 s6, 0x7c
	s_movk_i32 s22, 0xffef
	v_cmp_gt_u32_e64 s[30:31], 16, v56
	v_add_u32_e32 v56, 25, v55
	v_readlane_b32 s42, v254, 21
	v_mul_lo_u32 v51, v50, s6
	v_cmp_gt_u32_e64 s[6:7], 16, v55
	v_cmp_lt_u32_e64 s[22:23], s22, v55
	v_cmp_gt_u32_e64 s[34:35], 16, v56
	v_add_u32_e32 v56, 26, v55
	v_add_u32_e32 v55, 27, v55
	s_add_i32 s4, s42, s4
	v_cmp_gt_u32_e64 s[38:39], 16, v55
	v_add_u32_e32 v55, s83, v127
	v_add_u32_e32 v131, s4, v126
	v_lshl_add_u64 v[126:127], s[64:65], 1, v[52:53]
	v_lshl_add_u32 v51, v54, 4, v51
	v_lshlrev_b32_e32 v52, 2, v120
	v_sub_u32_e32 v51, v51, v52
	v_mul_u32_u24_e32 v52, 0x7c, v117
	s_mulk_i32 s2, 0x1f0
	v_sub_u32_e32 v51, v51, v52
	v_subrev_u32_e32 v51, s2, v51
	v_readlane_b32 s2, v254, 42
	s_mov_b32 s69, 0
	s_add_i32 s66, s5, -1
	v_add_u32_e32 v132, s2, v51
	v_add_u32_e32 v51, s33, v117
	v_sub_u32_e64 v51, v51, 4 clamp
	v_min_u32_e32 v51, 24, v51
	v_cmp_gt_u32_e64 s[36:37], 16, v56
	s_add_i32 s78, s78, 8
	v_sub_u32_e32 v133, v50, v51
	s_mov_b32 s4, 7
	v_add_u32_e32 v134, v55, v134
	s_add_i32 s98, s4, -5
	s_min_i32 s98, s98, s66
	s_add_i32 s98, s98, s78
	s_mov_b32 s100, 0xc000
	s_mov_b32 s101, 0
	v_lshl_add_u32 v196, s98, 6, v131
	v_mad_i64_i32 v[180:181], s[48:49], v196, s44, v[126:127]
	v_lshl_add_u64 v[184:185], v[180:181], 0, s[100:101]
	v_lshl_add_u64 v[188:189], v[184:185], 0, s[100:101]
	v_lshl_add_u64 v[192:193], v[188:189], 0, s[100:101]
	global_load_dwordx4 v[180:183], v[180:181], off
	global_load_dwordx4 v[184:187], v[184:185], off
	global_load_dwordx4 v[188:191], v[188:189], off
	global_load_dwordx4 v[192:195], v[192:193], off
	s_branch .LBB0_885

.LBB0_885:
	s_waitcnt vmcnt(0)
	ds_write_b128 v129, v[216:219] offset:4608
	ds_write_b128 v129, v[220:223] offset:5760
	ds_write_b128 v129, v[224:227] offset:6912
	ds_write_b128 v129, v[228:231] offset:8064
	ds_read_b128 v[50:53], v130 offset:4608
	ds_read_b128 v[98:101], v130 offset:4624
	ds_read_b128 v[102:105], v130 offset:4640
	ds_read_b128 v[106:109], v130 offset:4656
	s_waitcnt lgkmcnt(3)
	v_mfma_f32_32x32x16_bf16 v[50:65], v[50:53], v[82:85], 0
	s_add_i32 s42, s4, -5
	s_min_i32 s2, s42, s66
	s_add_i32 s2, s2, s78
	v_lshl_add_u32 v138, s2, 6, v131
	s_add_i32 s98, s4, -4
	s_min_i32 s98, s98, s66
	s_add_i32 s98, s98, s78
	s_mov_b32 s100, 0xc000
	s_mov_b32 s101, 0
	v_lshl_add_u32 v196, s98, 6, v131
	v_mad_i64_i32 v[216:217], s[48:49], v196, s44, v[126:127]
	v_lshl_add_u64 v[220:221], v[216:217], 0, s[100:101]
	v_lshl_add_u64 v[224:225], v[220:221], 0, s[100:101]
	v_lshl_add_u64 v[228:229], v[224:225], 0, s[100:101]
	global_load_dwordx4 v[216:219], v[216:217], off
	global_load_dwordx4 v[220:223], v[220:221], off
	global_load_dwordx4 v[224:227], v[224:225], off
	global_load_dwordx4 v[228:231], v[228:229], off
	s_waitcnt lgkmcnt(2)
	v_mfma_f32_32x32x16_bf16 v[50:65], v[98:101], v[86:89], v[50:65]
	s_nop 0
	v_add_u32_e32 v137, s4, v133
	v_add_u32_e32 v114, -7, v137
	v_add_u32_e32 v135, s69, v132
	v_mov_b32_e32 v115, 0xff800000
	s_waitcnt lgkmcnt(1)
	v_mfma_f32_32x32x16_bf16 v[50:65], v[102:105], v[90:93], v[50:65]
	s_nop 0
	s_nop 1
	s_nop 0
	s_nop 0
	s_waitcnt lgkmcnt(0)
	v_mfma_f32_32x32x16_bf16 v[50:65], v[106:109], v[94:97], v[50:65]
	s_nop 0
	s_nop 1
	s_nop 0
	s_nop 0
	s_nop 0
	s_nop 0
	s_nop 0
	s_nop 0
	v_cmp_gt_u32_e32 vcc, 8, v114
	ds_read_b32 v200, v135 offset:10400
	ds_read_b32 v201, v135 offset:10404
	ds_read_b32 v202, v135 offset:10408
	ds_read_b32 v203, v135 offset:10412
	ds_read_b32 v204, v135 offset:10432
	ds_read_b32 v205, v135 offset:10436
	ds_read_b32 v206, v135 offset:10440
	ds_read_b32 v207, v135 offset:10444
	ds_read_b32 v208, v135 offset:10464
	ds_read_b32 v209, v135 offset:10468
	ds_read_b32 v210, v135 offset:10472
	ds_read_b32 v211, v135 offset:10476
	ds_read_b32 v212, v135 offset:10496
	ds_read_b32 v213, v135 offset:10500
	ds_read_b32 v214, v135 offset:10504
	ds_read_b32 v215, v135 offset:10508
	s_waitcnt lgkmcnt(12)
	s_and_b64 s[48:49], vcc, s[6:7]
	v_add_f32_e32 v200, v34, v200
	v_cndmask_b32_e64 v115, v252, v200, s[48:49]
	s_and_b64 s[48:49], vcc, s[8:9]
	v_add_f32_e32 v201, v35, v201
	v_cndmask_b32_e64 v114, v252, v201, s[48:49]
	s_and_b64 s[48:49], vcc, s[10:11]
	v_add_f32_e32 v202, v36, v202
	v_cndmask_b32_e64 v35, v252, v202, s[48:49]
	s_and_b64 s[48:49], vcc, s[12:13]
	v_add_f32_e32 v203, v37, v203
	v_cndmask_b32_e64 v34, v252, v203, s[48:49]
	s_waitcnt lgkmcnt(8)
	s_and_b64 s[48:49], vcc, s[14:15]
	v_add_f32_e32 v204, v38, v204
	v_cndmask_b32_e64 v37, v252, v204, s[48:49]
	s_and_b64 s[48:49], vcc, s[16:17]
	v_add_f32_e32 v205, v39, v205
	v_cndmask_b32_e64 v36, v252, v205, s[48:49]
	s_and_b64 s[48:49], vcc, s[18:19]
	v_add_f32_e32 v206, v40, v206
	v_cndmask_b32_e64 v39, v252, v206, s[48:49]
	s_and_b64 s[48:49], vcc, s[20:21]
	v_add_f32_e32 v207, v41, v207
	v_cndmask_b32_e64 v38, v252, v207, s[48:49]
	s_waitcnt lgkmcnt(4)
	s_and_b64 s[48:49], vcc, s[22:23]
	v_add_f32_e32 v208, v42, v208
	v_cndmask_b32_e64 v116, v252, v208, s[48:49]
	s_and_b64 s[48:49], vcc, s[24:25]
	v_add_f32_e32 v209, v43, v209
	v_cndmask_b32_e64 v41, v252, v209, s[48:49]
	s_and_b64 s[48:49], vcc, s[26:27]
	v_add_f32_e32 v210, v44, v210
	v_cndmask_b32_e64 v118, v252, v210, s[48:49]
	s_and_b64 s[48:49], vcc, s[28:29]
	v_add_f32_e32 v211, v45, v211
	v_cndmask_b32_e64 v117, v252, v211, s[48:49]
	s_waitcnt lgkmcnt(0)
	s_and_b64 s[48:49], vcc, s[30:31]
	v_add_f32_e32 v212, v46, v212
	v_cndmask_b32_e64 v120, v252, v212, s[48:49]
	s_and_b64 s[48:49], vcc, s[34:35]
	v_add_f32_e32 v213, v47, v213
	v_cndmask_b32_e64 v119, v252, v213, s[48:49]
	s_and_b64 s[48:49], vcc, s[36:37]
	v_add_f32_e32 v214, v48, v214
	v_cndmask_b32_e64 v139, v252, v214, s[48:49]
	s_and_b64 s[48:49], vcc, s[38:39]
	v_add_f32_e32 v215, v49, v215
	v_cndmask_b32_e64 v121, v252, v215, s[48:49]
	v_max_f32_e32 v40, v114, v114
	v_max_f32_e32 v42, v115, v115
	v_max_f32_e32 v40, v42, v40
	v_max3_f32 v40, v40, v35, v34
	v_max3_f32 v40, v40, v37, v36
	v_max3_f32 v40, v40, v39, v38
	v_max3_f32 v40, v40, v116, v41
	v_max3_f32 v40, v40, v118, v117
	v_max3_f32 v40, v40, v120, v119
	v_max3_f32 v40, v40, v139, v121
	v_mov_b32_e32 v42, v40
	s_nop 1
	v_permlane32_swap_b32_e32 v40, v42
	v_max3_f32 v140, v123, v40, v42
	v_sub_f32_e32 v40, v115, v140
	v_exp_f32_e32 v40, v40
	v_sub_f32_e32 v42, v114, v140
	v_exp_f32_e32 v42, v42
	v_sub_f32_e32 v35, v35, v140
	v_exp_f32_e32 v35, v35
	v_sub_f32_e32 v34, v34, v140
	v_exp_f32_e32 v34, v34
	v_sub_f32_e32 v37, v37, v140
	v_add_f32_e32 v43, 0, v40
	v_exp_f32_e32 v37, v37
	v_sub_f32_e32 v36, v36, v140
	v_add_f32_e32 v43, v42, v43
	v_exp_f32_e32 v36, v36
	v_sub_f32_e32 v39, v39, v140
	v_add_f32_e32 v43, v35, v43
	v_exp_f32_e32 v39, v39
	v_sub_f32_e32 v38, v38, v140
	v_add_f32_e32 v43, v34, v43
	v_exp_f32_e32 v38, v38
	v_add_f32_e32 v43, v37, v43
	v_add_f32_e32 v43, v36, v43
	v_add_f32_e32 v43, v39, v43
	v_add_f32_e32 v46, v38, v43
	v_sub_f32_e32 v43, v116, v140
	v_exp_f32_e32 v43, v43
	v_sub_f32_e32 v41, v41, v140
	v_exp_f32_e32 v41, v41
	v_sub_f32_e32 v44, v118, v140
	v_exp_f32_e32 v44, v44
	v_sub_f32_e32 v45, v117, v140
	v_exp_f32_e32 v45, v45
	v_add_f32_e32 v46, v43, v46
	v_add_f32_e32 v46, v41, v46
	v_add_f32_e32 v46, v44, v46
	v_add_f32_e32 v114, v45, v46
	v_sub_f32_e32 v46, v120, v140
	v_exp_f32_e32 v46, v46
	v_sub_f32_e32 v47, v119, v140
	v_exp_f32_e32 v47, v47
	v_sub_f32_e32 v48, v139, v140
	v_exp_f32_e32 v48, v48
	v_sub_f32_e32 v49, v121, v140
	v_exp_f32_e32 v49, v49
	v_add_f32_e32 v114, v46, v114
	v_add_f32_e32 v114, v47, v114
	v_add_f32_e32 v114, v48, v114
	v_add_f32_e32 v139, v49, v114
	v_mov_b32_e32 v141, v139
	s_nop 1
	v_permlane32_swap_b32_e32 v139, v141
	v_cmp_gt_f32_e32 vcc, v140, v123
	s_cbranch_vccz .LBB0_919
	v_sub_f32_e32 v114, v123, v140
	v_exp_f32_e32 v114, v114
	s_nop 0
	v_mul_f32_e32 v136, v136, v114
	v_pk_mul_f32 v[32:33], v[32:33], v[114:115] op_sel_hi:[1,0]
	v_pk_mul_f32 v[30:31], v[30:31], v[114:115] op_sel_hi:[1,0]
	v_pk_mul_f32 v[28:29], v[28:29], v[114:115] op_sel_hi:[1,0]
	v_pk_mul_f32 v[26:27], v[26:27], v[114:115] op_sel_hi:[1,0]
	v_pk_mul_f32 v[24:25], v[24:25], v[114:115] op_sel_hi:[1,0]
	v_pk_mul_f32 v[22:23], v[22:23], v[114:115] op_sel_hi:[1,0]
	v_pk_mul_f32 v[20:21], v[20:21], v[114:115] op_sel_hi:[1,0]
	v_pk_mul_f32 v[18:19], v[18:19], v[114:115] op_sel_hi:[1,0]
	v_pk_mul_f32 v[16:17], v[16:17], v[114:115] op_sel_hi:[1,0]
	v_pk_mul_f32 v[14:15], v[14:15], v[114:115] op_sel_hi:[1,0]
	v_pk_mul_f32 v[12:13], v[12:13], v[114:115] op_sel_hi:[1,0]
	v_pk_mul_f32 v[10:11], v[10:11], v[114:115] op_sel_hi:[1,0]
	v_pk_mul_f32 v[8:9], v[8:9], v[114:115] op_sel_hi:[1,0]
	v_pk_mul_f32 v[6:7], v[6:7], v[114:115] op_sel_hi:[1,0]
	v_pk_mul_f32 v[4:5], v[4:5], v[114:115] op_sel_hi:[1,0]
	v_pk_mul_f32 v[2:3], v[2:3], v[114:115] op_sel_hi:[1,0]
.LBB0_919:
	v_cvt_pk_bf16_f32 v114, v40, v42
	v_cvt_pk_bf16_f32 v115, v35, v34
	v_cvt_pk_bf16_f32 v116, v37, v36
	v_cvt_pk_bf16_f32 v117, v39, v38
	v_cvt_pk_bf16_f32 v34, v43, v41
	v_cvt_pk_bf16_f32 v35, v44, v45
	v_cvt_pk_bf16_f32 v36, v46, v47
	v_cvt_pk_bf16_f32 v37, v48, v49
	ds_write_b128 v129, v[70:73]
	ds_write_b128 v129, v[66:69] offset:1152
	ds_write_b128 v129, v[74:77] offset:2304
	ds_write_b128 v129, v[78:81] offset:3456
	ds_read_b64_tr_b16 v[38:39], v134
	ds_read_b64_tr_b16 v[40:41], v134 offset:1152
	s_waitcnt lgkmcnt(0)
	v_mfma_f32_32x32x16_bf16 v[18:33], v[38:41], v[114:117], v[18:33]
	s_add_i32 s33, s4, -6
	ds_read_b64_tr_b16 v[42:43], v134 offset:2304
	ds_read_b64_tr_b16 v[44:45], v134 offset:3456
	ds_read_b64_tr_b16 v[48:49], v134 offset:1216
	ds_read_b64_tr_b16 v[46:47], v134 offset:64
	s_min_i32 s2, s33, s66
	s_add_i32 s2, s2, s78
	v_lshl_add_u32 v38, s2, 6, v131
	v_mad_i64_i32 v[74:75], s[48:49], v38, s44, v[124:125]
	s_waitcnt lgkmcnt(2)
	v_mfma_f32_32x32x16_bf16 v[18:33], v[42:45], v[34:37], v[18:33]
	v_add_co_u32_e32 v42, vcc, s46, v74
	ds_read_b64_tr_b16 v[40:41], v134 offset:3520
	ds_read_b64_tr_b16 v[38:39], v134 offset:2368
	v_addc_co_u32_e32 v43, vcc, 0, v75, vcc
	global_load_dwordx4 v[66:69], v[74:75], off
	global_load_dwordx4 v[70:73], v[42:43], off
	v_add_co_u32_e32 v42, vcc, s77, v74
	s_waitcnt lgkmcnt(2)
	v_mfma_f32_32x32x16_bf16 v[2:17], v[46:49], v[114:117], v[2:17]
	v_addc_co_u32_e32 v43, vcc, 0, v75, vcc
	v_add_co_u32_e32 v44, vcc, s45, v74
	s_add_i32 s2, s4, -4
	s_nop 0
	v_addc_co_u32_e32 v45, vcc, 0, v75, vcc
	global_load_dwordx4 v[114:117], v[42:43], off
	global_load_dwordx4 v[118:121], v[44:45], off
	s_nop 0
	ds_write_b128 v129, v[180:183] offset:4608
	s_nop 0
	ds_write_b128 v129, v[184:187] offset:5760
	s_nop 0
	ds_write_b128 v129, v[188:191] offset:6912
	s_nop 0
	ds_write_b128 v129, v[192:195] offset:8064
	s_waitcnt lgkmcnt(4)
	v_mfma_f32_32x32x16_bf16 v[2:17], v[38:41], v[34:37], v[2:17]
	ds_read_b128 v[34:37], v130 offset:4608
	ds_read_b128 v[74:77], v130 offset:4624
	s_min_i32 s43, s2, s66
	s_add_i32 s43, s43, s78
	v_lshl_add_u32 v123, s43, 6, v131
	s_add_i32 s98, s4, -3
	s_min_i32 s98, s98, s66
	s_add_i32 s98, s98, s78
	s_mov_b32 s100, 0xc000
	s_mov_b32 s101, 0
	v_lshl_add_u32 v196, s98, 6, v131
	v_mad_i64_i32 v[180:181], s[48:49], v196, s44, v[126:127]
	v_lshl_add_u64 v[184:185], v[180:181], 0, s[100:101]
	v_lshl_add_u64 v[188:189], v[184:185], 0, s[100:101]
	v_lshl_add_u64 v[192:193], v[188:189], 0, s[100:101]
	global_load_dwordx4 v[180:183], v[180:181], off
	global_load_dwordx4 v[184:187], v[184:185], off
	global_load_dwordx4 v[188:191], v[188:189], off
	global_load_dwordx4 v[192:195], v[192:193], off
	s_nop 0
	s_waitcnt lgkmcnt(1)
	v_mfma_f32_32x32x16_bf16 v[34:49], v[34:37], v[82:85], 0
	s_nop 0
	s_nop 0
	s_cmp_lt_i32 s33, s5
	s_nop 0
	s_nop 0
	s_waitcnt lgkmcnt(0)
	v_mfma_f32_32x32x16_bf16 v[34:49], v[74:77], v[86:89], v[34:49]
	ds_read_b128 v[74:77], v130 offset:4640
	ds_read_b128 v[98:101], v130 offset:4656
	s_waitcnt lgkmcnt(1)
	v_mfma_f32_32x32x16_bf16 v[34:49], v[74:77], v[90:93], v[34:49]
	s_nop 0
	s_nop 0
	s_nop 0
	s_nop 0
	s_nop 1
	s_nop 0
	s_nop 0
	s_nop 0
	s_waitcnt lgkmcnt(0)
	v_mfma_f32_32x32x16_bf16 v[34:49], v[98:101], v[94:97], v[34:49]
	v_mov_b32_e32 v98, 0xff800000
	s_cselect_b64 vcc, -1, 0
	v_cndmask_b32_e32 v99, v98, v58, vcc
	v_cndmask_b32_e32 v58, v98, v55, vcc
	v_cndmask_b32_e32 v55, v98, v54, vcc
	v_cndmask_b32_e32 v54, v98, v51, vcc
	v_add_u32_e32 v51, -6, v137
	v_cndmask_b32_e32 v65, v98, v65, vcc
	v_cndmask_b32_e32 v64, v98, v64, vcc
	v_cndmask_b32_e32 v63, v98, v63, vcc
	v_cndmask_b32_e32 v62, v98, v62, vcc
	v_cndmask_b32_e32 v61, v98, v61, vcc
	v_cndmask_b32_e32 v60, v98, v60, vcc
	v_cndmask_b32_e32 v59, v98, v59, vcc
	v_cndmask_b32_e32 v100, v98, v57, vcc
	v_cndmask_b32_e32 v57, v98, v56, vcc
	v_cndmask_b32_e32 v56, v98, v53, vcc
	v_cndmask_b32_e32 v53, v98, v52, vcc
	v_cndmask_b32_e32 v50, v98, v50, vcc
	v_cmp_gt_u32_e32 vcc, 8, v51
	ds_read_b32 v200, v135 offset:10524
	ds_read_b32 v201, v135 offset:10528
	ds_read_b32 v202, v135 offset:10532
	ds_read_b32 v203, v135 offset:10536
	ds_read_b32 v204, v135 offset:10556
	ds_read_b32 v205, v135 offset:10560
	ds_read_b32 v206, v135 offset:10564
	ds_read_b32 v207, v135 offset:10568
	ds_read_b32 v208, v135 offset:10588
	ds_read_b32 v209, v135 offset:10592
	ds_read_b32 v210, v135 offset:10596
	ds_read_b32 v211, v135 offset:10600
	ds_read_b32 v212, v135 offset:10620
	ds_read_b32 v213, v135 offset:10624
	ds_read_b32 v214, v135 offset:10628
	ds_read_b32 v215, v135 offset:10632
	s_waitcnt lgkmcnt(12)
	s_and_b64 s[48:49], vcc, s[6:7]
	v_add_f32_e32 v200, v50, v200
	v_cndmask_b32_e64 v51, v252, v200, s[48:49]
	s_and_b64 s[48:49], vcc, s[8:9]
	v_add_f32_e32 v201, v54, v201
	v_cndmask_b32_e64 v52, v252, v201, s[48:49]
	s_and_b64 s[48:49], vcc, s[10:11]
	v_add_f32_e32 v202, v53, v202
	v_cndmask_b32_e64 v98, v252, v202, s[48:49]
	s_and_b64 s[48:49], vcc, s[12:13]
	v_add_f32_e32 v203, v56, v203
	v_cndmask_b32_e64 v54, v252, v203, s[48:49]
	s_waitcnt lgkmcnt(8)
	s_and_b64 s[48:49], vcc, s[14:15]
	v_add_f32_e32 v204, v55, v204
	v_cndmask_b32_e64 v53, v252, v204, s[48:49]
	s_and_b64 s[48:49], vcc, s[16:17]
	v_add_f32_e32 v205, v58, v205
	v_cndmask_b32_e64 v56, v252, v205, s[48:49]
	s_and_b64 s[48:49], vcc, s[18:19]
	v_add_f32_e32 v206, v57, v206
	v_cndmask_b32_e64 v55, v252, v206, s[48:49]
	s_and_b64 s[48:49], vcc, s[20:21]
	v_add_f32_e32 v207, v100, v207
	v_cndmask_b32_e64 v58, v252, v207, s[48:49]
	s_waitcnt lgkmcnt(4)
	s_and_b64 s[48:49], vcc, s[22:23]
	v_add_f32_e32 v208, v99, v208
	v_cndmask_b32_e64 v57, v252, v208, s[48:49]
	s_and_b64 s[48:49], vcc, s[24:25]
	v_add_f32_e32 v209, v59, v209
	v_cndmask_b32_e64 v100, v252, v209, s[48:49]
	s_and_b64 s[48:49], vcc, s[26:27]
	v_add_f32_e32 v210, v60, v210
	v_cndmask_b32_e64 v99, v252, v210, s[48:49]
	s_and_b64 s[48:49], vcc, s[28:29]
	v_add_f32_e32 v211, v61, v211
	v_cndmask_b32_e64 v102, v252, v211, s[48:49]
	s_waitcnt lgkmcnt(0)
	s_and_b64 s[48:49], vcc, s[30:31]
	v_add_f32_e32 v212, v62, v212
	v_cndmask_b32_e64 v101, v252, v212, s[48:49]
	s_and_b64 s[48:49], vcc, s[34:35]
	v_add_f32_e32 v213, v63, v213
	v_cndmask_b32_e64 v104, v252, v213, s[48:49]
	s_and_b64 s[48:49], vcc, s[36:37]
	v_add_f32_e32 v214, v64, v214
	v_cndmask_b32_e64 v103, v252, v214, s[48:49]
	s_and_b64 s[48:49], vcc, s[38:39]
	v_add_f32_e32 v215, v65, v215
	v_cndmask_b32_e64 v105, v252, v215, s[48:49]
	v_max_f32_e32 v59, v52, v52
	v_max_f32_e32 v60, v51, v51
	v_max_f32_e32 v59, v60, v59
	v_max3_f32 v59, v59, v98, v54
	v_max3_f32 v59, v59, v53, v56
	v_max3_f32 v59, v59, v55, v58
	v_max3_f32 v59, v59, v57, v100
	v_max3_f32 v59, v59, v99, v102
	v_max3_f32 v59, v59, v101, v104
	v_max3_f32 v59, v59, v103, v105
	v_mov_b32_e32 v60, v59
	s_nop 1
	v_permlane32_swap_b32_e32 v59, v60
	v_add_f32_e32 v50, v139, v141
	v_max3_f32 v139, v140, v59, v60
	v_sub_f32_e32 v51, v51, v139
	v_exp_f32_e32 v59, v51
	v_sub_f32_e32 v51, v52, v139
	v_exp_f32_e32 v60, v51
	v_sub_f32_e32 v51, v98, v139
	v_exp_f32_e32 v61, v51
	v_sub_f32_e32 v51, v54, v139
	v_exp_f32_e32 v54, v51
	v_sub_f32_e32 v52, v53, v139
	v_add_f32_e32 v51, 0, v59
	v_exp_f32_e32 v53, v52
	v_sub_f32_e32 v52, v56, v139
	v_add_f32_e32 v51, v60, v51
	v_exp_f32_e32 v56, v52
	v_sub_f32_e32 v52, v55, v139
	v_add_f32_e32 v51, v61, v51
	v_exp_f32_e32 v55, v52
	v_sub_f32_e32 v52, v58, v139
	v_add_f32_e32 v51, v54, v51
	v_exp_f32_e32 v58, v52
	v_sub_f32_e32 v52, v57, v139
	v_add_f32_e32 v51, v53, v51
	v_exp_f32_e32 v57, v52
	v_sub_f32_e32 v52, v100, v139
	v_add_f32_e32 v51, v56, v51
	v_exp_f32_e32 v62, v52
	v_sub_f32_e32 v52, v99, v139
	v_add_f32_e32 v51, v55, v51
	v_exp_f32_e32 v63, v52
	v_sub_f32_e32 v52, v102, v139
	v_add_f32_e32 v51, v58, v51
	v_exp_f32_e32 v64, v52
	v_sub_f32_e32 v52, v101, v139
	v_add_f32_e32 v51, v57, v51
	v_exp_f32_e32 v65, v52
	v_sub_f32_e32 v52, v104, v139
	v_add_f32_e32 v51, v62, v51
	v_exp_f32_e32 v98, v52
	v_sub_f32_e32 v52, v103, v139
	v_add_f32_e32 v51, v63, v51
	v_exp_f32_e32 v99, v52
	v_sub_f32_e32 v52, v105, v139
	v_add_f32_e32 v51, v64, v51
	v_exp_f32_e32 v100, v52
	v_add_f32_e32 v51, v65, v51
	v_add_f32_e32 v51, v98, v51
	v_add_f32_e32 v51, v99, v51
	v_add_f32_e32 v51, v100, v51
	v_mov_b32_e32 v52, v51
	v_add_f32_e32 v50, v50, v136
	s_nop 0
	v_permlane32_swap_b32_e32 v51, v52
	v_cmp_gt_f32_e32 vcc, v139, v140
	s_cbranch_vccz .LBB0_953
	v_sub_f32_e32 v101, v140, v139
	v_exp_f32_e32 v102, v101
	s_nop 0
	v_mul_f32_e32 v50, v50, v102
	v_pk_mul_f32 v[32:33], v[32:33], v[102:103] op_sel_hi:[1,0]
	v_pk_mul_f32 v[30:31], v[30:31], v[102:103] op_sel_hi:[1,0]
	v_pk_mul_f32 v[28:29], v[28:29], v[102:103] op_sel_hi:[1,0]
	v_pk_mul_f32 v[26:27], v[26:27], v[102:103] op_sel_hi:[1,0]
	v_pk_mul_f32 v[24:25], v[24:25], v[102:103] op_sel_hi:[1,0]
	v_pk_mul_f32 v[22:23], v[22:23], v[102:103] op_sel_hi:[1,0]
	v_pk_mul_f32 v[20:21], v[20:21], v[102:103] op_sel_hi:[1,0]
	v_pk_mul_f32 v[18:19], v[18:19], v[102:103] op_sel_hi:[1,0]
	v_pk_mul_f32 v[16:17], v[16:17], v[102:103] op_sel_hi:[1,0]
	v_pk_mul_f32 v[14:15], v[14:15], v[102:103] op_sel_hi:[1,0]
	v_pk_mul_f32 v[12:13], v[12:13], v[102:103] op_sel_hi:[1,0]
	v_pk_mul_f32 v[10:11], v[10:11], v[102:103] op_sel_hi:[1,0]
	v_pk_mul_f32 v[8:9], v[8:9], v[102:103] op_sel_hi:[1,0]
	v_pk_mul_f32 v[6:7], v[6:7], v[102:103] op_sel_hi:[1,0]
	v_pk_mul_f32 v[4:5], v[4:5], v[102:103] op_sel_hi:[1,0]
	v_pk_mul_f32 v[2:3], v[2:3], v[102:103] op_sel_hi:[1,0]
.LBB0_953:
	v_cvt_pk_bf16_f32 v102, v59, v60
	v_cvt_pk_bf16_f32 v103, v61, v54
	v_cvt_pk_bf16_f32 v104, v53, v56
	v_cvt_pk_bf16_f32 v105, v55, v58
	v_cvt_pk_bf16_f32 v54, v57, v62
	v_cvt_pk_bf16_f32 v55, v63, v64
	v_cvt_pk_bf16_f32 v56, v65, v98
	v_cvt_pk_bf16_f32 v57, v99, v100
	s_waitcnt vmcnt(7)
	ds_write_b128 v129, v[66:69]
	s_waitcnt vmcnt(6)
	ds_write_b128 v129, v[70:73] offset:1152
	s_waitcnt vmcnt(5)
	ds_write_b128 v129, v[114:117] offset:2304
	s_waitcnt vmcnt(4)
	ds_write_b128 v129, v[118:121] offset:3456
	ds_read_b64_tr_b16 v[58:59], v134
	ds_read_b64_tr_b16 v[60:61], v134 offset:1152
	s_waitcnt lgkmcnt(0)
	v_mfma_f32_32x32x16_bf16 v[18:33], v[58:61], v[102:105], v[18:33]
	v_mad_i64_i32 v[62:63], s[48:49], v138, s44, 0
	v_lshl_add_u64 v[114:115], v[124:125], 0, v[62:63]
	ds_read_b64_tr_b16 v[62:63], v134 offset:2304
	ds_read_b64_tr_b16 v[64:65], v134 offset:3456
	ds_read_b64_tr_b16 v[100:101], v134 offset:1216
	ds_read_b64_tr_b16 v[98:99], v134 offset:64
	v_add_co_u32_e32 v58, vcc, s46, v114
	v_add_f32_e32 v51, v51, v52
	s_nop 0
	v_addc_co_u32_e32 v59, vcc, 0, v115, vcc
	s_waitcnt lgkmcnt(2)
	v_mfma_f32_32x32x16_bf16 v[18:33], v[62:65], v[54:57], v[18:33]
	v_add_co_u32_e32 v62, vcc, s77, v114
	global_load_dwordx4 v[66:69], v[114:115], off
	global_load_dwordx4 v[70:73], v[58:59], off
	v_addc_co_u32_e32 v63, vcc, 0, v115, vcc
	v_add_co_u32_e32 v64, vcc, s45, v114
	ds_read_b64_tr_b16 v[60:61], v134 offset:3520
	ds_read_b64_tr_b16 v[58:59], v134 offset:2368
	v_addc_co_u32_e32 v65, vcc, 0, v115, vcc
	s_waitcnt lgkmcnt(2)
	v_mfma_f32_32x32x16_bf16 v[2:17], v[98:101], v[102:105], v[2:17]
	global_load_dwordx4 v[98:101], v[62:63], off
	global_load_dwordx4 v[102:105], v[64:65], off
	v_add_f32_e32 v136, v51, v50
	s_cmp_ge_i32 s42, s5
	s_mov_b64 s[64:65], -1
	s_waitcnt lgkmcnt(0)
	v_mfma_f32_32x32x16_bf16 v[2:17], v[58:61], v[54:57], v[2:17]
	s_cbranch_scc1 .LBB0_884
	s_nop 0
	ds_write_b128 v129, v[216:219] offset:4608
	s_nop 0
	ds_write_b128 v129, v[220:223] offset:5760
	s_nop 0
	ds_write_b128 v129, v[224:227] offset:6912
	s_nop 0
	ds_write_b128 v129, v[228:231] offset:8064
	ds_read_b128 v[50:53], v130 offset:4608
	ds_read_b128 v[74:77], v130 offset:4624
	ds_read_b128 v[78:81], v130 offset:4640
	ds_read_b128 v[106:109], v130 offset:4656
	s_waitcnt lgkmcnt(3)
	v_mfma_f32_32x32x16_bf16 v[50:65], v[50:53], v[82:85], 0
	s_add_i32 s43, s4, -3
	s_min_i32 s33, s43, s66
	s_add_i32 s33, s33, s78
	v_lshl_add_u32 v115, s33, 6, v131
	s_add_i32 s98, s4, -2
	s_min_i32 s98, s98, s66
	s_add_i32 s98, s98, s78
	s_mov_b32 s100, 0xc000
	s_mov_b32 s101, 0
	v_lshl_add_u32 v196, s98, 6, v131
	v_mad_i64_i32 v[216:217], s[48:49], v196, s44, v[126:127]
	v_lshl_add_u64 v[220:221], v[216:217], 0, s[100:101]
	v_lshl_add_u64 v[224:225], v[220:221], 0, s[100:101]
	v_lshl_add_u64 v[228:229], v[224:225], 0, s[100:101]
	global_load_dwordx4 v[216:219], v[216:217], off
	global_load_dwordx4 v[220:223], v[220:221], off
	global_load_dwordx4 v[224:227], v[224:225], off
	global_load_dwordx4 v[228:231], v[228:229], off
	s_waitcnt lgkmcnt(2)
	v_mfma_f32_32x32x16_bf16 v[50:65], v[74:77], v[86:89], v[50:65]
	s_nop 0
	v_add_u32_e32 v114, -5, v137
	v_mov_b32_e32 v116, 0xff800000
	s_waitcnt lgkmcnt(1)
	v_mfma_f32_32x32x16_bf16 v[50:65], v[78:81], v[90:93], v[50:65]
	s_nop 0
	s_nop 1
	s_nop 0
	s_nop 0
	s_waitcnt lgkmcnt(0)
	v_mfma_f32_32x32x16_bf16 v[50:65], v[106:109], v[94:97], v[50:65]
	s_nop 0
	s_nop 1
	s_nop 0
	s_nop 0
	s_nop 0
	s_nop 0
	s_nop 0
	s_nop 0
	v_cmp_gt_u32_e32 vcc, 8, v114
	ds_read_b32 v200, v135 offset:10648
	ds_read_b32 v201, v135 offset:10652
	ds_read_b32 v202, v135 offset:10656
	ds_read_b32 v203, v135 offset:10660
	ds_read_b32 v204, v135 offset:10680
	ds_read_b32 v205, v135 offset:10684
	ds_read_b32 v206, v135 offset:10688
	ds_read_b32 v207, v135 offset:10692
	ds_read_b32 v208, v135 offset:10712
	ds_read_b32 v209, v135 offset:10716
	ds_read_b32 v210, v135 offset:10720
	ds_read_b32 v211, v135 offset:10724
	ds_read_b32 v212, v135 offset:10744
	ds_read_b32 v213, v135 offset:10748
	ds_read_b32 v214, v135 offset:10752
	ds_read_b32 v215, v135 offset:10756
	s_waitcnt lgkmcnt(12)
	s_and_b64 s[48:49], vcc, s[6:7]
	v_add_f32_e32 v200, v34, v200
	v_cndmask_b32_e64 v116, v252, v200, s[48:49]
	s_and_b64 s[48:49], vcc, s[8:9]
	v_add_f32_e32 v201, v35, v201
	v_cndmask_b32_e64 v114, v252, v201, s[48:49]
	s_and_b64 s[48:49], vcc, s[10:11]
	v_add_f32_e32 v202, v36, v202
	v_cndmask_b32_e64 v35, v252, v202, s[48:49]
	s_and_b64 s[48:49], vcc, s[12:13]
	v_add_f32_e32 v203, v37, v203
	v_cndmask_b32_e64 v34, v252, v203, s[48:49]
	s_waitcnt lgkmcnt(8)
	s_and_b64 s[48:49], vcc, s[14:15]
	v_add_f32_e32 v204, v38, v204
	v_cndmask_b32_e64 v37, v252, v204, s[48:49]
	s_and_b64 s[48:49], vcc, s[16:17]
	v_add_f32_e32 v205, v39, v205
	v_cndmask_b32_e64 v36, v252, v205, s[48:49]
	s_and_b64 s[48:49], vcc, s[18:19]
	v_add_f32_e32 v206, v40, v206
	v_cndmask_b32_e64 v39, v252, v206, s[48:49]
	s_and_b64 s[48:49], vcc, s[20:21]
	v_add_f32_e32 v207, v41, v207
	v_cndmask_b32_e64 v38, v252, v207, s[48:49]
	s_waitcnt lgkmcnt(4)
	s_and_b64 s[48:49], vcc, s[22:23]
	v_add_f32_e32 v208, v42, v208
	v_cndmask_b32_e64 v119, v252, v208, s[48:49]
	s_and_b64 s[48:49], vcc, s[24:25]
	v_add_f32_e32 v209, v43, v209
	v_cndmask_b32_e64 v118, v252, v209, s[48:49]
	s_and_b64 s[48:49], vcc, s[26:27]
	v_add_f32_e32 v210, v44, v210
	v_cndmask_b32_e64 v121, v252, v210, s[48:49]
	s_and_b64 s[48:49], vcc, s[28:29]
	v_add_f32_e32 v211, v45, v211
	v_cndmask_b32_e64 v120, v252, v211, s[48:49]
	s_waitcnt lgkmcnt(0)
	s_and_b64 s[48:49], vcc, s[30:31]
	v_add_f32_e32 v212, v46, v212
	v_cndmask_b32_e64 v140, v252, v212, s[48:49]
	s_and_b64 s[48:49], vcc, s[34:35]
	v_add_f32_e32 v213, v47, v213
	v_cndmask_b32_e64 v138, v252, v213, s[48:49]
	s_and_b64 s[48:49], vcc, s[36:37]
	v_add_f32_e32 v214, v48, v214
	v_cndmask_b32_e64 v142, v252, v214, s[48:49]
	s_and_b64 s[48:49], vcc, s[38:39]
	v_add_f32_e32 v215, v49, v215
	v_cndmask_b32_e64 v141, v252, v215, s[48:49]
	v_max_f32_e32 v40, v114, v114
	v_max_f32_e32 v41, v116, v116
	v_max_f32_e32 v40, v41, v40
	v_max3_f32 v40, v40, v35, v34
	v_max3_f32 v40, v40, v37, v36
	v_max3_f32 v40, v40, v39, v38
	v_max3_f32 v40, v40, v119, v118
	v_max3_f32 v40, v40, v121, v120
	v_max3_f32 v40, v40, v140, v138
	v_max3_f32 v40, v40, v142, v141
	v_mov_b32_e32 v41, v40
	s_nop 1
	v_permlane32_swap_b32_e32 v40, v41
	v_max3_f32 v117, v139, v40, v41
	v_sub_f32_e32 v40, v116, v117
	v_exp_f32_e32 v40, v40
	v_sub_f32_e32 v41, v114, v117
	v_exp_f32_e32 v41, v41
	v_sub_f32_e32 v35, v35, v117
	v_exp_f32_e32 v35, v35
	v_sub_f32_e32 v34, v34, v117
	v_exp_f32_e32 v34, v34
	v_sub_f32_e32 v37, v37, v117
	v_add_f32_e32 v42, 0, v40
	v_exp_f32_e32 v37, v37
	v_sub_f32_e32 v36, v36, v117
	v_add_f32_e32 v42, v41, v42
	v_exp_f32_e32 v36, v36
	v_sub_f32_e32 v39, v39, v117
	v_add_f32_e32 v42, v35, v42
	v_exp_f32_e32 v39, v39
	v_sub_f32_e32 v38, v38, v117
	v_add_f32_e32 v42, v34, v42
	v_exp_f32_e32 v38, v38
	v_add_f32_e32 v42, v37, v42
	v_add_f32_e32 v42, v36, v42
	v_add_f32_e32 v42, v39, v42
	v_add_f32_e32 v46, v38, v42
	v_sub_f32_e32 v42, v119, v117
	v_exp_f32_e32 v42, v42
	v_sub_f32_e32 v43, v118, v117
	v_exp_f32_e32 v43, v43
	v_sub_f32_e32 v44, v121, v117
	v_exp_f32_e32 v44, v44
	v_sub_f32_e32 v45, v120, v117
	v_exp_f32_e32 v45, v45
	v_add_f32_e32 v46, v42, v46
	v_add_f32_e32 v46, v43, v46
	v_add_f32_e32 v46, v44, v46
	v_add_f32_e32 v114, v45, v46
	v_sub_f32_e32 v46, v140, v117
	v_exp_f32_e32 v46, v46
	v_sub_f32_e32 v47, v138, v117
	v_exp_f32_e32 v47, v47
	v_sub_f32_e32 v48, v142, v117
	v_exp_f32_e32 v48, v48
	v_sub_f32_e32 v49, v141, v117
	v_exp_f32_e32 v49, v49
	v_add_f32_e32 v114, v46, v114
	v_add_f32_e32 v114, v47, v114
	v_add_f32_e32 v114, v48, v114
	v_add_f32_e32 v116, v49, v114
	v_mov_b32_e32 v118, v116
	s_nop 1
	v_permlane32_swap_b32_e32 v116, v118
	v_cmp_gt_f32_e32 vcc, v117, v139
	s_cbranch_vccz .LBB0_988
	v_sub_f32_e32 v114, v139, v117
	v_exp_f32_e32 v114, v114
	s_nop 0
	v_mul_f32_e32 v136, v136, v114
	v_pk_mul_f32 v[32:33], v[32:33], v[114:115] op_sel_hi:[1,0]
	v_pk_mul_f32 v[30:31], v[30:31], v[114:115] op_sel_hi:[1,0]
	v_pk_mul_f32 v[28:29], v[28:29], v[114:115] op_sel_hi:[1,0]
	v_pk_mul_f32 v[26:27], v[26:27], v[114:115] op_sel_hi:[1,0]
	v_pk_mul_f32 v[24:25], v[24:25], v[114:115] op_sel_hi:[1,0]
	v_pk_mul_f32 v[22:23], v[22:23], v[114:115] op_sel_hi:[1,0]
	v_pk_mul_f32 v[20:21], v[20:21], v[114:115] op_sel_hi:[1,0]
	v_pk_mul_f32 v[18:19], v[18:19], v[114:115] op_sel_hi:[1,0]
	v_pk_mul_f32 v[16:17], v[16:17], v[114:115] op_sel_hi:[1,0]
	v_pk_mul_f32 v[14:15], v[14:15], v[114:115] op_sel_hi:[1,0]
	v_pk_mul_f32 v[12:13], v[12:13], v[114:115] op_sel_hi:[1,0]
	v_pk_mul_f32 v[10:11], v[10:11], v[114:115] op_sel_hi:[1,0]
	v_pk_mul_f32 v[8:9], v[8:9], v[114:115] op_sel_hi:[1,0]
	v_pk_mul_f32 v[6:7], v[6:7], v[114:115] op_sel_hi:[1,0]
	v_pk_mul_f32 v[4:5], v[4:5], v[114:115] op_sel_hi:[1,0]
	v_pk_mul_f32 v[2:3], v[2:3], v[114:115] op_sel_hi:[1,0]
.LBB0_988:
	v_cvt_pk_bf16_f32 v138, v40, v41
	v_cvt_pk_bf16_f32 v139, v35, v34
	v_cvt_pk_bf16_f32 v140, v37, v36
	v_cvt_pk_bf16_f32 v141, v39, v38
	v_cvt_pk_bf16_f32 v34, v42, v43
	v_cvt_pk_bf16_f32 v35, v44, v45
	v_cvt_pk_bf16_f32 v36, v46, v47
	v_cvt_pk_bf16_f32 v37, v48, v49
	s_waitcnt vmcnt(7)
	ds_write_b128 v129, v[66:69]
	s_waitcnt vmcnt(6)
	ds_write_b128 v129, v[70:73] offset:1152
	s_waitcnt vmcnt(5)
	ds_write_b128 v129, v[98:101] offset:2304
	s_waitcnt vmcnt(4)
	ds_write_b128 v129, v[102:105] offset:3456
	ds_read_b64_tr_b16 v[38:39], v134
	ds_read_b64_tr_b16 v[40:41], v134 offset:1152
	ds_read_b64_tr_b16 v[44:45], v134 offset:1216
	ds_read_b64_tr_b16 v[42:43], v134 offset:64
	s_waitcnt lgkmcnt(2)
	v_mfma_f32_32x32x16_bf16 v[18:33], v[38:41], v[138:141], v[18:33]
	ds_read_b64_tr_b16 v[38:39], v134 offset:2304
	ds_read_b64_tr_b16 v[40:41], v134 offset:3456
	v_mad_i64_i32 v[46:47], s[48:49], v123, s44, 0
	v_lshl_add_u64 v[98:99], v[124:125], 0, v[46:47]
	ds_read_b64_tr_b16 v[48:49], v134 offset:3520
	ds_read_b64_tr_b16 v[46:47], v134 offset:2368
	s_add_i32 s42, s4, -2
	s_min_i32 s33, s42, s66
	s_waitcnt lgkmcnt(2)
	v_mfma_f32_32x32x16_bf16 v[18:33], v[38:41], v[34:37], v[18:33]
	v_add_co_u32_e32 v38, vcc, s46, v98
	s_add_i32 s33, s33, s78
	s_nop 0
	v_addc_co_u32_e32 v39, vcc, 0, v99, vcc
	global_load_dwordx4 v[66:69], v[98:99], off
	global_load_dwordx4 v[70:73], v[38:39], off
	v_add_co_u32_e32 v38, vcc, s77, v98
	v_mfma_f32_32x32x16_bf16 v[2:17], v[42:45], v[138:141], v[2:17]
	s_nop 0
	v_addc_co_u32_e32 v39, vcc, 0, v99, vcc
	v_add_co_u32_e32 v40, vcc, s45, v98
	v_lshl_add_u32 v114, s33, 6, v131
	s_nop 0
	v_addc_co_u32_e32 v41, vcc, 0, v99, vcc
	global_load_dwordx4 v[98:101], v[38:39], off
	global_load_dwordx4 v[102:105], v[40:41], off
	s_nop 0
	ds_write_b128 v129, v[180:183] offset:4608
	s_nop 0
	ds_write_b128 v129, v[184:187] offset:5760
	s_nop 0
	ds_write_b128 v129, v[188:191] offset:6912
	s_nop 0
	ds_write_b128 v129, v[192:195] offset:8064
	s_waitcnt lgkmcnt(4)
	v_mfma_f32_32x32x16_bf16 v[2:17], v[46:49], v[34:37], v[2:17]
	ds_read_b128 v[34:37], v130 offset:4608
	ds_read_b128 v[74:77], v130 offset:4624
	s_add_i32 s98, s4, -1
	s_min_i32 s98, s98, s66
	s_add_i32 s98, s98, s78
	s_mov_b32 s100, 0xc000
	s_mov_b32 s101, 0
	v_lshl_add_u32 v196, s98, 6, v131
	v_mad_i64_i32 v[180:181], s[48:49], v196, s44, v[126:127]
	v_lshl_add_u64 v[184:185], v[180:181], 0, s[100:101]
	v_lshl_add_u64 v[188:189], v[184:185], 0, s[100:101]
	v_lshl_add_u64 v[192:193], v[188:189], 0, s[100:101]
	global_load_dwordx4 v[180:183], v[180:181], off
	global_load_dwordx4 v[184:187], v[184:185], off
	global_load_dwordx4 v[188:191], v[188:189], off
	global_load_dwordx4 v[192:195], v[192:193], off
	s_nop 0
	s_cmp_lt_i32 s2, s5
	s_nop 0
	s_nop 0
	s_waitcnt lgkmcnt(1)
	v_mfma_f32_32x32x16_bf16 v[34:49], v[34:37], v[82:85], 0
	s_nop 0
	v_mov_b32_e32 v119, 0xff800000
	s_nop 0
	s_nop 0
	s_nop 0
	s_waitcnt lgkmcnt(0)
	v_mfma_f32_32x32x16_bf16 v[34:49], v[74:77], v[86:89], v[34:49]
	ds_read_b128 v[74:77], v130 offset:4640
	ds_read_b128 v[138:141], v130 offset:4656
	s_nop 0
	s_cselect_b64 vcc, -1, 0
	s_nop 0
	v_cndmask_b32_e32 v120, v119, v58, vcc
	v_cndmask_b32_e32 v58, v119, v55, vcc
	s_waitcnt lgkmcnt(1)
	v_mfma_f32_32x32x16_bf16 v[34:49], v[74:77], v[90:93], v[34:49]
	s_nop 0
	s_nop 0
	s_nop 0
	s_nop 0
	s_nop 0
	s_nop 0
	s_nop 0
	v_cndmask_b32_e32 v55, v119, v54, vcc
	v_cndmask_b32_e32 v54, v119, v51, vcc
	v_add_u32_e32 v51, -4, v137
	v_cndmask_b32_e32 v65, v119, v65, vcc
	v_cndmask_b32_e32 v64, v119, v64, vcc
	s_waitcnt lgkmcnt(0)
	v_mfma_f32_32x32x16_bf16 v[34:49], v[138:141], v[94:97], v[34:49]
	v_cndmask_b32_e32 v63, v119, v63, vcc
	v_cndmask_b32_e32 v62, v119, v62, vcc
	v_cndmask_b32_e32 v61, v119, v61, vcc
	v_cndmask_b32_e32 v60, v119, v60, vcc
	v_cndmask_b32_e32 v59, v119, v59, vcc
	v_cndmask_b32_e32 v121, v119, v57, vcc
	v_cndmask_b32_e32 v57, v119, v56, vcc
	v_cndmask_b32_e32 v56, v119, v53, vcc
	v_cndmask_b32_e32 v53, v119, v52, vcc
	v_cndmask_b32_e32 v50, v119, v50, vcc
	v_cmp_gt_u32_e32 vcc, 8, v51
	ds_read_b32 v200, v135 offset:10772
	ds_read_b32 v201, v135 offset:10776
	ds_read_b32 v202, v135 offset:10780
	ds_read_b32 v203, v135 offset:10784
	ds_read_b32 v204, v135 offset:10804
	ds_read_b32 v205, v135 offset:10808
	ds_read_b32 v206, v135 offset:10812
	ds_read_b32 v207, v135 offset:10816
	ds_read_b32 v208, v135 offset:10836
	ds_read_b32 v209, v135 offset:10840
	ds_read_b32 v210, v135 offset:10844
	ds_read_b32 v211, v135 offset:10848
	ds_read_b32 v212, v135 offset:10868
	ds_read_b32 v213, v135 offset:10872
	ds_read_b32 v214, v135 offset:10876
	ds_read_b32 v215, v135 offset:10880
	s_waitcnt lgkmcnt(12)
	s_and_b64 s[48:49], vcc, s[6:7]
	v_add_f32_e32 v200, v50, v200
	v_cndmask_b32_e64 v51, v252, v200, s[48:49]
	s_and_b64 s[48:49], vcc, s[8:9]
	v_add_f32_e32 v201, v54, v201
	v_cndmask_b32_e64 v52, v252, v201, s[48:49]
	s_and_b64 s[48:49], vcc, s[10:11]
	v_add_f32_e32 v202, v53, v202
	v_cndmask_b32_e64 v119, v252, v202, s[48:49]
	s_and_b64 s[48:49], vcc, s[12:13]
	v_add_f32_e32 v203, v56, v203
	v_cndmask_b32_e64 v54, v252, v203, s[48:49]
	s_waitcnt lgkmcnt(8)
	s_and_b64 s[48:49], vcc, s[14:15]
	v_add_f32_e32 v204, v55, v204
	v_cndmask_b32_e64 v53, v252, v204, s[48:49]
	s_and_b64 s[48:49], vcc, s[16:17]
	v_add_f32_e32 v205, v58, v205
	v_cndmask_b32_e64 v56, v252, v205, s[48:49]
	s_and_b64 s[48:49], vcc, s[18:19]
	v_add_f32_e32 v206, v57, v206
	v_cndmask_b32_e64 v55, v252, v206, s[48:49]
	s_and_b64 s[48:49], vcc, s[20:21]
	v_add_f32_e32 v207, v121, v207
	v_cndmask_b32_e64 v58, v252, v207, s[48:49]
	s_waitcnt lgkmcnt(4)
	s_and_b64 s[48:49], vcc, s[22:23]
	v_add_f32_e32 v208, v120, v208
	v_cndmask_b32_e64 v57, v252, v208, s[48:49]
	s_and_b64 s[48:49], vcc, s[24:25]
	v_add_f32_e32 v209, v59, v209
	v_cndmask_b32_e64 v121, v252, v209, s[48:49]
	s_and_b64 s[48:49], vcc, s[26:27]
	v_add_f32_e32 v210, v60, v210
	v_cndmask_b32_e64 v120, v252, v210, s[48:49]
	s_and_b64 s[48:49], vcc, s[28:29]
	v_add_f32_e32 v211, v61, v211
	v_cndmask_b32_e64 v138, v252, v211, s[48:49]
	s_waitcnt lgkmcnt(0)
	s_and_b64 s[48:49], vcc, s[30:31]
	v_add_f32_e32 v212, v62, v212
	v_cndmask_b32_e64 v123, v252, v212, s[48:49]
	s_and_b64 s[48:49], vcc, s[34:35]
	v_add_f32_e32 v213, v63, v213
	v_cndmask_b32_e64 v140, v252, v213, s[48:49]
	s_and_b64 s[48:49], vcc, s[36:37]
	v_add_f32_e32 v214, v64, v214
	v_cndmask_b32_e64 v139, v252, v214, s[48:49]
	s_and_b64 s[48:49], vcc, s[38:39]
	v_add_f32_e32 v215, v65, v215
	v_cndmask_b32_e64 v141, v252, v215, s[48:49]
	v_max_f32_e32 v59, v52, v52
	v_max_f32_e32 v60, v51, v51
	v_max_f32_e32 v59, v60, v59
	v_max3_f32 v59, v59, v119, v54
	v_max3_f32 v59, v59, v53, v56
	v_max3_f32 v59, v59, v55, v58
	v_max3_f32 v59, v59, v57, v121
	v_max3_f32 v59, v59, v120, v138
	v_max3_f32 v59, v59, v123, v140
	v_max3_f32 v59, v59, v139, v141
	v_mov_b32_e32 v60, v59
	s_nop 1
	v_permlane32_swap_b32_e32 v59, v60
	v_add_f32_e32 v50, v116, v118
	v_max3_f32 v116, v117, v59, v60
	v_sub_f32_e32 v51, v51, v116
	v_exp_f32_e32 v59, v51
	v_sub_f32_e32 v51, v52, v116
	v_exp_f32_e32 v60, v51
	v_sub_f32_e32 v51, v119, v116
	v_exp_f32_e32 v61, v51
	v_sub_f32_e32 v51, v54, v116
	v_exp_f32_e32 v54, v51
	v_sub_f32_e32 v52, v53, v116
	v_add_f32_e32 v51, 0, v59
	v_exp_f32_e32 v53, v52
	v_sub_f32_e32 v52, v56, v116
	v_add_f32_e32 v51, v60, v51
	v_exp_f32_e32 v56, v52
	v_sub_f32_e32 v52, v55, v116
	v_add_f32_e32 v51, v61, v51
	v_exp_f32_e32 v55, v52
	v_sub_f32_e32 v52, v58, v116
	v_add_f32_e32 v51, v54, v51
	v_exp_f32_e32 v58, v52
	v_sub_f32_e32 v52, v57, v116
	v_add_f32_e32 v51, v53, v51
	v_exp_f32_e32 v57, v52
	v_sub_f32_e32 v52, v121, v116
	v_add_f32_e32 v51, v56, v51
	v_exp_f32_e32 v62, v52
	v_sub_f32_e32 v52, v120, v116
	v_add_f32_e32 v51, v55, v51
	v_exp_f32_e32 v63, v52
	v_sub_f32_e32 v52, v138, v116
	v_add_f32_e32 v51, v58, v51
	v_exp_f32_e32 v64, v52
	v_sub_f32_e32 v52, v123, v116
	v_add_f32_e32 v51, v57, v51
	v_exp_f32_e32 v65, v52
	v_sub_f32_e32 v52, v140, v116
	v_add_f32_e32 v51, v62, v51
	v_exp_f32_e32 v118, v52
	v_sub_f32_e32 v52, v139, v116
	v_add_f32_e32 v51, v63, v51
	v_exp_f32_e32 v119, v52
	v_sub_f32_e32 v52, v141, v116
	v_add_f32_e32 v51, v64, v51
	v_exp_f32_e32 v120, v52
	v_add_f32_e32 v51, v65, v51
	v_add_f32_e32 v51, v118, v51
	v_add_f32_e32 v51, v119, v51
	v_add_f32_e32 v51, v120, v51
	v_mov_b32_e32 v52, v51
	v_add_f32_e32 v50, v50, v136
	s_nop 0
	v_permlane32_swap_b32_e32 v51, v52
	v_cmp_gt_f32_e32 vcc, v116, v117
	s_cbranch_vccz .LBB0_1022
	v_sub_f32_e32 v117, v117, v116
	v_exp_f32_e32 v136, v117
	s_nop 0
	v_mul_f32_e32 v50, v50, v136
	v_pk_mul_f32 v[32:33], v[32:33], v[136:137] op_sel_hi:[1,0]
	v_pk_mul_f32 v[30:31], v[30:31], v[136:137] op_sel_hi:[1,0]
	v_pk_mul_f32 v[28:29], v[28:29], v[136:137] op_sel_hi:[1,0]
	v_pk_mul_f32 v[26:27], v[26:27], v[136:137] op_sel_hi:[1,0]
	v_pk_mul_f32 v[24:25], v[24:25], v[136:137] op_sel_hi:[1,0]
	v_pk_mul_f32 v[22:23], v[22:23], v[136:137] op_sel_hi:[1,0]
	v_pk_mul_f32 v[20:21], v[20:21], v[136:137] op_sel_hi:[1,0]
	v_pk_mul_f32 v[18:19], v[18:19], v[136:137] op_sel_hi:[1,0]
	v_pk_mul_f32 v[16:17], v[16:17], v[136:137] op_sel_hi:[1,0]
	v_pk_mul_f32 v[14:15], v[14:15], v[136:137] op_sel_hi:[1,0]
	v_pk_mul_f32 v[12:13], v[12:13], v[136:137] op_sel_hi:[1,0]
	v_pk_mul_f32 v[10:11], v[10:11], v[136:137] op_sel_hi:[1,0]
	v_pk_mul_f32 v[8:9], v[8:9], v[136:137] op_sel_hi:[1,0]
	v_pk_mul_f32 v[6:7], v[6:7], v[136:137] op_sel_hi:[1,0]
	v_pk_mul_f32 v[4:5], v[4:5], v[136:137] op_sel_hi:[1,0]
	v_pk_mul_f32 v[2:3], v[2:3], v[136:137] op_sel_hi:[1,0]
.LBB0_1022:
	v_cvt_pk_bf16_f32 v138, v59, v60
	v_cvt_pk_bf16_f32 v139, v61, v54
	v_cvt_pk_bf16_f32 v140, v53, v56
	v_cvt_pk_bf16_f32 v141, v55, v58
	v_cvt_pk_bf16_f32 v54, v57, v62
	v_cvt_pk_bf16_f32 v55, v63, v64
	v_cvt_pk_bf16_f32 v56, v65, v118
	v_cvt_pk_bf16_f32 v57, v119, v120
	s_waitcnt vmcnt(7)
	ds_write_b128 v129, v[66:69]
	s_waitcnt vmcnt(6)
	ds_write_b128 v129, v[70:73] offset:1152
	s_waitcnt vmcnt(5)
	ds_write_b128 v129, v[98:101] offset:2304
	s_waitcnt vmcnt(4)
	ds_write_b128 v129, v[102:105] offset:3456
	ds_read_b64_tr_b16 v[58:59], v134
	ds_read_b64_tr_b16 v[60:61], v134 offset:1152
	s_waitcnt lgkmcnt(0)
	v_mfma_f32_32x32x16_bf16 v[18:33], v[58:61], v[138:141], v[18:33]
	v_mad_i64_i32 v[62:63], s[48:49], v115, s44, 0
	v_lshl_add_u64 v[102:103], v[124:125], 0, v[62:63]
	ds_read_b64_tr_b16 v[62:63], v134 offset:2304
	ds_read_b64_tr_b16 v[64:65], v134 offset:3456
	ds_read_b64_tr_b16 v[100:101], v134 offset:1216
	ds_read_b64_tr_b16 v[98:99], v134 offset:64
	v_add_co_u32_e32 v58, vcc, s46, v102
	v_add_f32_e32 v51, v51, v52
	s_nop 0
	v_addc_co_u32_e32 v59, vcc, 0, v103, vcc
	s_waitcnt lgkmcnt(2)
	v_mfma_f32_32x32x16_bf16 v[18:33], v[62:65], v[54:57], v[18:33]
	v_add_co_u32_e32 v62, vcc, s77, v102
	global_load_dwordx4 v[66:69], v[102:103], off
	global_load_dwordx4 v[70:73], v[58:59], off
	v_addc_co_u32_e32 v63, vcc, 0, v103, vcc
	v_add_co_u32_e32 v64, vcc, s45, v102
	ds_read_b64_tr_b16 v[60:61], v134 offset:3520
	ds_read_b64_tr_b16 v[58:59], v134 offset:2368
	v_addc_co_u32_e32 v65, vcc, 0, v103, vcc
	s_waitcnt lgkmcnt(2)
	v_mfma_f32_32x32x16_bf16 v[2:17], v[98:101], v[138:141], v[2:17]
	global_load_dwordx4 v[98:101], v[62:63], off
	global_load_dwordx4 v[102:105], v[64:65], off
	v_add_f32_e32 v136, v51, v50
	s_cmp_ge_i32 s43, s5
	s_waitcnt lgkmcnt(0)
	v_mfma_f32_32x32x16_bf16 v[2:17], v[58:61], v[54:57], v[2:17]
	s_cbranch_scc1 .LBB0_884
	s_nop 0
	ds_write_b128 v129, v[216:219] offset:4608
	s_nop 0
	ds_write_b128 v129, v[220:223] offset:5760
	s_nop 0
	ds_write_b128 v129, v[224:227] offset:6912
	s_nop 0
	ds_write_b128 v129, v[228:231] offset:8064
	ds_read_b128 v[50:53], v130 offset:4608
	ds_read_b128 v[74:77], v130 offset:4624
	ds_read_b128 v[78:81], v130 offset:4640
	ds_read_b128 v[106:109], v130 offset:4656
	s_waitcnt lgkmcnt(3)
	v_mfma_f32_32x32x16_bf16 v[50:65], v[50:53], v[82:85], 0
	s_add_i32 s2, s4, -1
	s_min_i32 s33, s2, s66
	s_add_i32 s33, s33, s78
	v_lshl_add_u32 v138, s33, 6, v131
	s_add_i32 s98, s4, 0
	s_min_i32 s98, s98, s66
	s_add_i32 s98, s98, s78
	s_mov_b32 s100, 0xc000
	s_mov_b32 s101, 0
	v_lshl_add_u32 v196, s98, 6, v131
	v_mad_i64_i32 v[216:217], s[48:49], v196, s44, v[126:127]
	v_lshl_add_u64 v[220:221], v[216:217], 0, s[100:101]
	v_lshl_add_u64 v[224:225], v[220:221], 0, s[100:101]
	v_lshl_add_u64 v[228:229], v[224:225], 0, s[100:101]
	global_load_dwordx4 v[216:219], v[216:217], off
	global_load_dwordx4 v[220:223], v[220:221], off
	global_load_dwordx4 v[224:227], v[224:225], off
	global_load_dwordx4 v[228:231], v[228:229], off
	s_waitcnt lgkmcnt(2)
	v_mfma_f32_32x32x16_bf16 v[50:65], v[74:77], v[86:89], v[50:65]
	s_nop 0
	v_add_u32_e32 v115, -3, v137
	v_mov_b32_e32 v117, 0xff800000
	s_waitcnt lgkmcnt(1)
	v_mfma_f32_32x32x16_bf16 v[50:65], v[78:81], v[90:93], v[50:65]
	s_nop 0
	s_nop 1
	s_nop 0
	s_nop 0
	s_waitcnt lgkmcnt(0)
	v_mfma_f32_32x32x16_bf16 v[50:65], v[106:109], v[94:97], v[50:65]
	s_nop 0
	s_nop 1
	s_nop 0
	s_nop 0
	s_nop 0
	s_nop 0
	s_nop 0
	s_nop 0
	v_cmp_gt_u32_e32 vcc, 8, v115
	ds_read_b32 v200, v135 offset:10896
	ds_read_b32 v201, v135 offset:10900
	ds_read_b32 v202, v135 offset:10904
	ds_read_b32 v203, v135 offset:10908
	ds_read_b32 v204, v135 offset:10928
	ds_read_b32 v205, v135 offset:10932
	ds_read_b32 v206, v135 offset:10936
	ds_read_b32 v207, v135 offset:10940
	ds_read_b32 v208, v135 offset:10960
	ds_read_b32 v209, v135 offset:10964
	ds_read_b32 v210, v135 offset:10968
	ds_read_b32 v211, v135 offset:10972
	ds_read_b32 v212, v135 offset:10992
	ds_read_b32 v213, v135 offset:10996
	ds_read_b32 v214, v135 offset:11000
	ds_read_b32 v215, v135 offset:11004
	s_waitcnt lgkmcnt(12)
	s_and_b64 s[48:49], vcc, s[6:7]
	v_add_f32_e32 v200, v34, v200
	v_cndmask_b32_e64 v117, v252, v200, s[48:49]
	s_and_b64 s[48:49], vcc, s[8:9]
	v_add_f32_e32 v201, v35, v201
	v_cndmask_b32_e64 v115, v252, v201, s[48:49]
	s_and_b64 s[48:49], vcc, s[10:11]
	v_add_f32_e32 v202, v36, v202
	v_cndmask_b32_e64 v35, v252, v202, s[48:49]
	s_and_b64 s[48:49], vcc, s[12:13]
	v_add_f32_e32 v203, v37, v203
	v_cndmask_b32_e64 v34, v252, v203, s[48:49]
	s_waitcnt lgkmcnt(8)
	s_and_b64 s[48:49], vcc, s[14:15]
	v_add_f32_e32 v204, v38, v204
	v_cndmask_b32_e64 v37, v252, v204, s[48:49]
	s_and_b64 s[48:49], vcc, s[16:17]
	v_add_f32_e32 v205, v39, v205
	v_cndmask_b32_e64 v36, v252, v205, s[48:49]
	s_and_b64 s[48:49], vcc, s[18:19]
	v_add_f32_e32 v206, v40, v206
	v_cndmask_b32_e64 v39, v252, v206, s[48:49]
	s_and_b64 s[48:49], vcc, s[20:21]
	v_add_f32_e32 v207, v41, v207
	v_cndmask_b32_e64 v38, v252, v207, s[48:49]
	s_waitcnt lgkmcnt(4)
	s_and_b64 s[48:49], vcc, s[22:23]
	v_add_f32_e32 v208, v42, v208
	v_cndmask_b32_e64 v119, v252, v208, s[48:49]
	s_and_b64 s[48:49], vcc, s[24:25]
	v_add_f32_e32 v209, v43, v209
	v_cndmask_b32_e64 v118, v252, v209, s[48:49]
	s_and_b64 s[48:49], vcc, s[26:27]
	v_add_f32_e32 v210, v44, v210
	v_cndmask_b32_e64 v121, v252, v210, s[48:49]
	s_and_b64 s[48:49], vcc, s[28:29]
	v_add_f32_e32 v211, v45, v211
	v_cndmask_b32_e64 v120, v252, v211, s[48:49]
	s_waitcnt lgkmcnt(0)
	s_and_b64 s[48:49], vcc, s[30:31]
	v_add_f32_e32 v212, v46, v212
	v_cndmask_b32_e64 v140, v252, v212, s[48:49]
	s_and_b64 s[48:49], vcc, s[34:35]
	v_add_f32_e32 v213, v47, v213
	v_cndmask_b32_e64 v123, v252, v213, s[48:49]
	s_and_b64 s[48:49], vcc, s[36:37]
	v_add_f32_e32 v214, v48, v214
	v_cndmask_b32_e64 v142, v252, v214, s[48:49]
	s_and_b64 s[48:49], vcc, s[38:39]
	v_add_f32_e32 v215, v49, v215
	v_cndmask_b32_e64 v141, v252, v215, s[48:49]
	v_max_f32_e32 v40, v115, v115
	v_max_f32_e32 v41, v117, v117
	v_max_f32_e32 v40, v41, v40
	v_max3_f32 v40, v40, v35, v34
	v_max3_f32 v40, v40, v37, v36
	v_max3_f32 v40, v40, v39, v38
	v_max3_f32 v40, v40, v119, v118
	v_max3_f32 v40, v40, v121, v120
	v_max3_f32 v40, v40, v140, v123
	v_max3_f32 v40, v40, v142, v141
	v_mov_b32_e32 v41, v40
	s_nop 1
	v_permlane32_swap_b32_e32 v40, v41
	v_max3_f32 v139, v116, v40, v41
	v_sub_f32_e32 v40, v117, v139
	v_exp_f32_e32 v40, v40
	v_sub_f32_e32 v41, v115, v139
	v_exp_f32_e32 v41, v41
	v_sub_f32_e32 v35, v35, v139
	v_exp_f32_e32 v35, v35
	v_sub_f32_e32 v34, v34, v139
	v_exp_f32_e32 v34, v34
	v_sub_f32_e32 v37, v37, v139
	v_add_f32_e32 v42, 0, v40
	v_exp_f32_e32 v37, v37
	v_sub_f32_e32 v36, v36, v139
	v_add_f32_e32 v42, v41, v42
	v_exp_f32_e32 v36, v36
	v_sub_f32_e32 v39, v39, v139
	v_add_f32_e32 v42, v35, v42
	v_exp_f32_e32 v39, v39
	v_sub_f32_e32 v38, v38, v139
	v_add_f32_e32 v42, v34, v42
	v_exp_f32_e32 v38, v38
	v_add_f32_e32 v42, v37, v42
	v_add_f32_e32 v42, v36, v42
	v_add_f32_e32 v42, v39, v42
	v_add_f32_e32 v46, v38, v42
	v_sub_f32_e32 v42, v119, v139
	v_exp_f32_e32 v42, v42
	v_sub_f32_e32 v43, v118, v139
	v_exp_f32_e32 v43, v43
	v_sub_f32_e32 v44, v121, v139
	v_exp_f32_e32 v44, v44
	v_sub_f32_e32 v45, v120, v139
	v_exp_f32_e32 v45, v45
	v_add_f32_e32 v46, v42, v46
	v_add_f32_e32 v46, v43, v46
	v_add_f32_e32 v46, v44, v46
	v_add_f32_e32 v115, v45, v46
	v_sub_f32_e32 v46, v140, v139
	v_exp_f32_e32 v46, v46
	v_sub_f32_e32 v47, v123, v139
	v_exp_f32_e32 v47, v47
	v_sub_f32_e32 v48, v142, v139
	v_exp_f32_e32 v48, v48
	v_sub_f32_e32 v49, v141, v139
	v_exp_f32_e32 v49, v49
	v_add_f32_e32 v115, v46, v115
	v_add_f32_e32 v115, v47, v115
	v_add_f32_e32 v115, v48, v115
	v_add_f32_e32 v123, v49, v115
	v_mov_b32_e32 v140, v123
	s_nop 1
	v_permlane32_swap_b32_e32 v123, v140
	v_cmp_gt_f32_e32 vcc, v139, v116
	s_cbranch_vccz .LBB0_1057
	v_sub_f32_e32 v115, v116, v139
	v_exp_f32_e32 v116, v115
	s_nop 0
	v_mul_f32_e32 v136, v136, v116
	v_pk_mul_f32 v[32:33], v[32:33], v[116:117] op_sel_hi:[1,0]
	v_pk_mul_f32 v[30:31], v[30:31], v[116:117] op_sel_hi:[1,0]
	v_pk_mul_f32 v[28:29], v[28:29], v[116:117] op_sel_hi:[1,0]
	v_pk_mul_f32 v[26:27], v[26:27], v[116:117] op_sel_hi:[1,0]
	v_pk_mul_f32 v[24:25], v[24:25], v[116:117] op_sel_hi:[1,0]
	v_pk_mul_f32 v[22:23], v[22:23], v[116:117] op_sel_hi:[1,0]
	v_pk_mul_f32 v[20:21], v[20:21], v[116:117] op_sel_hi:[1,0]
	v_pk_mul_f32 v[18:19], v[18:19], v[116:117] op_sel_hi:[1,0]
	v_pk_mul_f32 v[16:17], v[16:17], v[116:117] op_sel_hi:[1,0]
	v_pk_mul_f32 v[14:15], v[14:15], v[116:117] op_sel_hi:[1,0]
	v_pk_mul_f32 v[12:13], v[12:13], v[116:117] op_sel_hi:[1,0]
	v_pk_mul_f32 v[10:11], v[10:11], v[116:117] op_sel_hi:[1,0]
	v_pk_mul_f32 v[8:9], v[8:9], v[116:117] op_sel_hi:[1,0]
	v_pk_mul_f32 v[6:7], v[6:7], v[116:117] op_sel_hi:[1,0]
	v_pk_mul_f32 v[4:5], v[4:5], v[116:117] op_sel_hi:[1,0]
	v_pk_mul_f32 v[2:3], v[2:3], v[116:117] op_sel_hi:[1,0]
.LBB0_1057:
	v_cvt_pk_bf16_f32 v116, v40, v41
	v_cvt_pk_bf16_f32 v117, v35, v34
	v_cvt_pk_bf16_f32 v118, v37, v36
	v_cvt_pk_bf16_f32 v119, v39, v38
	v_cvt_pk_bf16_f32 v34, v42, v43
	v_cvt_pk_bf16_f32 v35, v44, v45
	v_cvt_pk_bf16_f32 v36, v46, v47
	v_cvt_pk_bf16_f32 v37, v48, v49
	s_waitcnt vmcnt(7)
	ds_write_b128 v129, v[66:69]
	s_waitcnt vmcnt(6)
	ds_write_b128 v129, v[70:73] offset:1152
	s_waitcnt vmcnt(5)
	ds_write_b128 v129, v[98:101] offset:2304
	s_waitcnt vmcnt(4)
	ds_write_b128 v129, v[102:105] offset:3456
	ds_read_b64_tr_b16 v[38:39], v134
	ds_read_b64_tr_b16 v[40:41], v134 offset:1152
	ds_read_b64_tr_b16 v[44:45], v134 offset:1216
	ds_read_b64_tr_b16 v[42:43], v134 offset:64
	s_waitcnt lgkmcnt(2)
	v_mfma_f32_32x32x16_bf16 v[18:33], v[38:41], v[116:119], v[18:33]
	ds_read_b64_tr_b16 v[38:39], v134 offset:2304
	ds_read_b64_tr_b16 v[40:41], v134 offset:3456
	v_mad_i64_i32 v[46:47], s[48:49], v114, s44, 0
	v_lshl_add_u64 v[98:99], v[124:125], 0, v[46:47]
	ds_read_b64_tr_b16 v[48:49], v134 offset:3520
	ds_read_b64_tr_b16 v[46:47], v134 offset:2368
	s_min_i32 s33, s4, s66
	s_add_i32 s33, s33, s78
	s_waitcnt lgkmcnt(2)
	v_mfma_f32_32x32x16_bf16 v[18:33], v[38:41], v[34:37], v[18:33]
	v_add_co_u32_e32 v38, vcc, s46, v98
	s_cmp_lt_i32 s42, s5
	s_nop 0
	v_addc_co_u32_e32 v39, vcc, 0, v99, vcc
	global_load_dwordx4 v[66:69], v[98:99], off
	global_load_dwordx4 v[70:73], v[38:39], off
	v_add_co_u32_e32 v38, vcc, s77, v98
	v_mfma_f32_32x32x16_bf16 v[2:17], v[42:45], v[116:119], v[2:17]
	s_nop 0
	v_addc_co_u32_e32 v39, vcc, 0, v99, vcc
	v_add_co_u32_e32 v40, vcc, s45, v98
	s_nop 1
	v_addc_co_u32_e32 v41, vcc, 0, v99, vcc
	global_load_dwordx4 v[114:117], v[38:39], off
	global_load_dwordx4 v[118:121], v[40:41], off
	s_nop 0
	ds_write_b128 v129, v[180:183] offset:4608
	s_nop 0
	ds_write_b128 v129, v[184:187] offset:5760
	s_nop 0
	ds_write_b128 v129, v[188:191] offset:6912
	s_nop 0
	ds_write_b128 v129, v[192:195] offset:8064
	s_waitcnt lgkmcnt(4)
	v_mfma_f32_32x32x16_bf16 v[2:17], v[46:49], v[34:37], v[2:17]
	ds_read_b128 v[34:37], v130 offset:4608
	ds_read_b128 v[74:77], v130 offset:4624
	s_waitcnt lgkmcnt(1)
	v_mfma_f32_32x32x16_bf16 v[34:49], v[34:37], v[82:85], 0
	s_waitcnt lgkmcnt(0)
	v_mfma_f32_32x32x16_bf16 v[34:49], v[74:77], v[86:89], v[34:49]
	ds_read_b128 v[74:77], v130 offset:4640
	ds_read_b128 v[78:81], v130 offset:4656
	s_waitcnt lgkmcnt(1)
	v_mfma_f32_32x32x16_bf16 v[34:49], v[74:77], v[90:93], v[34:49]
	v_lshl_add_u32 v74, s33, 6, v131
	s_nop 0
	s_nop 0
	s_nop 1
	s_nop 0
	s_nop 0
	s_nop 0
	s_nop 0
	s_waitcnt lgkmcnt(0)
	v_mfma_f32_32x32x16_bf16 v[34:49], v[78:81], v[94:97], v[34:49]
	s_nop 0
	s_nop 0
	s_nop 1
	s_nop 0
	s_nop 0
	s_nop 0
	v_mov_b32_e32 v74, 0xff800000
	s_cselect_b64 vcc, -1, 0
	s_add_i32 s98, s4, 1
	s_min_i32 s98, s98, s66
	s_add_i32 s98, s98, s78
	s_mov_b32 s100, 0xc000
	s_mov_b32 s101, 0
	v_lshl_add_u32 v196, s98, 6, v131
	v_mad_i64_i32 v[180:181], s[48:49], v196, s44, v[126:127]
	v_lshl_add_u64 v[184:185], v[180:181], 0, s[100:101]
	v_lshl_add_u64 v[188:189], v[184:185], 0, s[100:101]
	v_lshl_add_u64 v[192:193], v[188:189], 0, s[100:101]
	global_load_dwordx4 v[180:183], v[180:181], off
	global_load_dwordx4 v[184:187], v[184:185], off
	global_load_dwordx4 v[188:191], v[188:189], off
	global_load_dwordx4 v[192:195], v[192:193], off
	v_cndmask_b32_e32 v75, v74, v58, vcc
	v_cndmask_b32_e32 v58, v74, v55, vcc
	v_cndmask_b32_e32 v55, v74, v54, vcc
	v_cndmask_b32_e32 v54, v74, v51, vcc
	v_add_u32_e32 v51, -2, v137
	v_cndmask_b32_e32 v65, v74, v65, vcc
	v_cndmask_b32_e32 v64, v74, v64, vcc
	v_cndmask_b32_e32 v63, v74, v63, vcc
	v_cndmask_b32_e32 v62, v74, v62, vcc
	v_cndmask_b32_e32 v61, v74, v61, vcc
	v_cndmask_b32_e32 v60, v74, v60, vcc
	v_cndmask_b32_e32 v59, v74, v59, vcc
	v_cndmask_b32_e32 v76, v74, v57, vcc
	v_cndmask_b32_e32 v57, v74, v56, vcc
	v_cndmask_b32_e32 v56, v74, v53, vcc
	v_cndmask_b32_e32 v53, v74, v52, vcc
	v_cndmask_b32_e32 v50, v74, v50, vcc
	v_cmp_gt_u32_e32 vcc, 8, v51
	ds_read_b32 v200, v135 offset:11020
	ds_read_b32 v201, v135 offset:11024
	ds_read_b32 v202, v135 offset:11028
	ds_read_b32 v203, v135 offset:11032
	ds_read_b32 v204, v135 offset:11052
	ds_read_b32 v205, v135 offset:11056
	ds_read_b32 v206, v135 offset:11060
	ds_read_b32 v207, v135 offset:11064
	ds_read_b32 v208, v135 offset:11084
	ds_read_b32 v209, v135 offset:11088
	ds_read_b32 v210, v135 offset:11092
	ds_read_b32 v211, v135 offset:11096
	ds_read_b32 v212, v135 offset:11116
	ds_read_b32 v213, v135 offset:11120
	ds_read_b32 v214, v135 offset:11124
	ds_read_b32 v215, v135 offset:11128
	s_waitcnt lgkmcnt(12)
	s_and_b64 s[42:43], vcc, s[6:7]
	v_add_f32_e32 v200, v50, v200
	v_cndmask_b32_e64 v51, v252, v200, s[42:43]
	s_and_b64 s[42:43], vcc, s[8:9]
	v_add_f32_e32 v201, v54, v201
	v_cndmask_b32_e64 v52, v252, v201, s[42:43]
	s_and_b64 s[42:43], vcc, s[10:11]
	v_add_f32_e32 v202, v53, v202
	v_cndmask_b32_e64 v74, v252, v202, s[42:43]
	s_and_b64 s[42:43], vcc, s[12:13]
	v_add_f32_e32 v203, v56, v203
	v_cndmask_b32_e64 v54, v252, v203, s[42:43]
	s_waitcnt lgkmcnt(8)
	s_and_b64 s[42:43], vcc, s[14:15]
	v_add_f32_e32 v204, v55, v204
	v_cndmask_b32_e64 v53, v252, v204, s[42:43]
	s_and_b64 s[42:43], vcc, s[16:17]
	v_add_f32_e32 v205, v58, v205
	v_cndmask_b32_e64 v56, v252, v205, s[42:43]
	s_and_b64 s[42:43], vcc, s[18:19]
	v_add_f32_e32 v206, v57, v206
	v_cndmask_b32_e64 v55, v252, v206, s[42:43]
	s_and_b64 s[42:43], vcc, s[20:21]
	v_add_f32_e32 v207, v76, v207
	v_cndmask_b32_e64 v58, v252, v207, s[42:43]
	s_waitcnt lgkmcnt(4)
	s_and_b64 s[42:43], vcc, s[22:23]
	v_add_f32_e32 v208, v75, v208
	v_cndmask_b32_e64 v57, v252, v208, s[42:43]
	s_and_b64 s[42:43], vcc, s[24:25]
	v_add_f32_e32 v209, v59, v209
	v_cndmask_b32_e64 v76, v252, v209, s[42:43]
	s_and_b64 s[42:43], vcc, s[26:27]
	v_add_f32_e32 v210, v60, v210
	v_cndmask_b32_e64 v75, v252, v210, s[42:43]
	s_and_b64 s[42:43], vcc, s[28:29]
	v_add_f32_e32 v211, v61, v211
	v_cndmask_b32_e64 v78, v252, v211, s[42:43]
	s_waitcnt lgkmcnt(0)
	s_and_b64 s[42:43], vcc, s[30:31]
	v_add_f32_e32 v212, v62, v212
	v_cndmask_b32_e64 v77, v252, v212, s[42:43]
	s_and_b64 s[42:43], vcc, s[34:35]
	v_add_f32_e32 v213, v63, v213
	v_cndmask_b32_e64 v80, v252, v213, s[42:43]
	s_and_b64 s[42:43], vcc, s[36:37]
	v_add_f32_e32 v214, v64, v214
	v_cndmask_b32_e64 v79, v252, v214, s[42:43]
	s_and_b64 s[42:43], vcc, s[38:39]
	v_add_f32_e32 v215, v65, v215
	v_cndmask_b32_e64 v81, v252, v215, s[42:43]
	v_max_f32_e32 v59, v52, v52
	v_max_f32_e32 v60, v51, v51
	v_max_f32_e32 v59, v60, v59
	v_max3_f32 v59, v59, v74, v54
	v_max3_f32 v59, v59, v53, v56
	v_max3_f32 v59, v59, v55, v58
	v_max3_f32 v59, v59, v57, v76
	v_max3_f32 v59, v59, v75, v78
	v_max3_f32 v59, v59, v77, v80
	v_max3_f32 v59, v59, v79, v81
	v_mov_b32_e32 v60, v59
	s_nop 1
	v_permlane32_swap_b32_e32 v59, v60
	v_add_f32_e32 v50, v123, v140
	v_max3_f32 v123, v139, v59, v60
	v_sub_f32_e32 v51, v51, v123
	v_exp_f32_e32 v59, v51
	v_sub_f32_e32 v51, v52, v123
	v_exp_f32_e32 v60, v51
	v_sub_f32_e32 v51, v74, v123
	v_exp_f32_e32 v61, v51
	v_sub_f32_e32 v51, v54, v123
	v_exp_f32_e32 v54, v51
	v_sub_f32_e32 v52, v53, v123
	v_add_f32_e32 v51, 0, v59
	v_exp_f32_e32 v53, v52
	v_sub_f32_e32 v52, v56, v123
	v_add_f32_e32 v51, v60, v51
	v_exp_f32_e32 v56, v52
	v_sub_f32_e32 v52, v55, v123
	v_add_f32_e32 v51, v61, v51
	v_exp_f32_e32 v55, v52
	v_sub_f32_e32 v52, v58, v123
	v_add_f32_e32 v51, v54, v51
	v_exp_f32_e32 v58, v52
	v_sub_f32_e32 v52, v57, v123
	v_add_f32_e32 v51, v53, v51
	v_exp_f32_e32 v57, v52
	v_sub_f32_e32 v52, v76, v123
	v_add_f32_e32 v51, v56, v51
	v_exp_f32_e32 v62, v52
	v_sub_f32_e32 v52, v75, v123
	v_add_f32_e32 v51, v55, v51
	v_exp_f32_e32 v63, v52
	v_sub_f32_e32 v52, v78, v123
	v_add_f32_e32 v51, v58, v51
	v_exp_f32_e32 v64, v52
	v_sub_f32_e32 v52, v77, v123
	v_add_f32_e32 v51, v57, v51
	v_exp_f32_e32 v65, v52
	v_sub_f32_e32 v52, v80, v123
	v_add_f32_e32 v51, v62, v51
	v_exp_f32_e32 v74, v52
	v_sub_f32_e32 v52, v79, v123
	v_add_f32_e32 v51, v63, v51
	v_exp_f32_e32 v75, v52
	v_sub_f32_e32 v52, v81, v123
	v_add_f32_e32 v51, v64, v51
	v_exp_f32_e32 v76, v52
	v_add_f32_e32 v51, v65, v51
	v_add_f32_e32 v51, v74, v51
	v_add_f32_e32 v51, v75, v51
	v_add_f32_e32 v51, v76, v51
	v_mov_b32_e32 v52, v51
	v_add_f32_e32 v50, v50, v136
	s_nop 0
	v_permlane32_swap_b32_e32 v51, v52
	v_cmp_gt_f32_e32 vcc, v123, v139
	s_cbranch_vccz .LBB0_1091
	v_sub_f32_e32 v77, v139, v123
	v_exp_f32_e32 v78, v77
	s_nop 0
	v_mul_f32_e32 v50, v50, v78
	v_pk_mul_f32 v[32:33], v[32:33], v[78:79] op_sel_hi:[1,0]
	v_pk_mul_f32 v[30:31], v[30:31], v[78:79] op_sel_hi:[1,0]
	v_pk_mul_f32 v[28:29], v[28:29], v[78:79] op_sel_hi:[1,0]
	v_pk_mul_f32 v[26:27], v[26:27], v[78:79] op_sel_hi:[1,0]
	v_pk_mul_f32 v[24:25], v[24:25], v[78:79] op_sel_hi:[1,0]
	v_pk_mul_f32 v[22:23], v[22:23], v[78:79] op_sel_hi:[1,0]
	v_pk_mul_f32 v[20:21], v[20:21], v[78:79] op_sel_hi:[1,0]
	v_pk_mul_f32 v[18:19], v[18:19], v[78:79] op_sel_hi:[1,0]
	v_pk_mul_f32 v[16:17], v[16:17], v[78:79] op_sel_hi:[1,0]
	v_pk_mul_f32 v[14:15], v[14:15], v[78:79] op_sel_hi:[1,0]
	v_pk_mul_f32 v[12:13], v[12:13], v[78:79] op_sel_hi:[1,0]
	v_pk_mul_f32 v[10:11], v[10:11], v[78:79] op_sel_hi:[1,0]
	v_pk_mul_f32 v[8:9], v[8:9], v[78:79] op_sel_hi:[1,0]
	v_pk_mul_f32 v[6:7], v[6:7], v[78:79] op_sel_hi:[1,0]
	v_pk_mul_f32 v[4:5], v[4:5], v[78:79] op_sel_hi:[1,0]
	v_pk_mul_f32 v[2:3], v[2:3], v[78:79] op_sel_hi:[1,0]

	.amdhsa_kernel _Z14fwd_megakernel4Args
		.amdhsa_group_segment_fixed_size 0
		.amdhsa_private_segment_fixed_size 0
		.amdhsa_kernarg_size 408
		.amdhsa_user_sgpr_count 2
		.amdhsa_user_sgpr_dispatch_ptr 0
		.amdhsa_user_sgpr_queue_ptr 0
		.amdhsa_user_sgpr_kernarg_segment_ptr 1
		.amdhsa_user_sgpr_dispatch_id 0
		.amdhsa_user_sgpr_kernarg_preload_length 0
		.amdhsa_user_sgpr_kernarg_preload_offset 0
		.amdhsa_user_sgpr_private_segment_size 0
		.amdhsa_uses_dynamic_stack 0
		.amdhsa_enable_private_segment 0
		.amdhsa_system_sgpr_workgroup_id_x 1
		.amdhsa_system_sgpr_workgroup_id_y 0
		.amdhsa_system_sgpr_workgroup_id_z 0
		.amdhsa_system_sgpr_workgroup_info 0
		.amdhsa_system_vgpr_workitem_id 2
		.amdhsa_next_free_vgpr 255
		.amdhsa_next_free_sgpr 102
		.amdhsa_accum_offset 256
		.amdhsa_reserve_vcc 1
		.amdhsa_float_round_mode_32 0
		.amdhsa_float_round_mode_16_64 0
		.amdhsa_float_denorm_mode_32 3
		.amdhsa_float_denorm_mode_16_64 3
		.amdhsa_dx10_clamp 1
		.amdhsa_ieee_mode 1
		.amdhsa_fp16_overflow 0
		.amdhsa_tg_split 0
		.amdhsa_exception_fp_ieee_invalid_op 0
		.amdhsa_exception_fp_denorm_src 0
		.amdhsa_exception_fp_ieee_div_zero 0
		.amdhsa_exception_fp_ieee_overflow 0
		.amdhsa_exception_fp_ieee_underflow 0
		.amdhsa_exception_fp_ieee_inexact 0
		.amdhsa_exception_int_div_zero 0
	.end_amdhsa_kernel

amdhsa.kernels:
  - .agpr_count:     0
    .args:
      - .offset:         0
        .size:           152
        .value_kind:     by_value
      - .offset:         152
        .size:           4
        .value_kind:     hidden_block_count_x
      - .offset:         156
        .size:           4
        .value_kind:     hidden_block_count_y
      - .offset:         160
        .size:           4
        .value_kind:     hidden_block_count_z
      - .offset:         164
        .size:           2
        .value_kind:     hidden_group_size_x
      - .offset:         166
        .size:           2
        .value_kind:     hidden_group_size_y
      - .offset:         168
        .size:           2
        .value_kind:     hidden_group_size_z
      - .offset:         170
        .size:           2
        .value_kind:     hidden_remainder_x
      - .offset:         172
        .size:           2
        .value_kind:     hidden_remainder_y
      - .offset:         174
        .size:           2
        .value_kind:     hidden_remainder_z
      - .offset:         192
        .size:           8
        .value_kind:     hidden_global_offset_x
      - .offset:         200
        .size:           8
        .value_kind:     hidden_global_offset_y
      - .offset:         208
        .size:           8
        .value_kind:     hidden_global_offset_z
      - .offset:         216
        .size:           2
        .value_kind:     hidden_grid_dims
      - .offset:         240
        .size:           8
        .value_kind:     hidden_multigrid_sync_arg
      - .offset:         272
        .size:           4
        .value_kind:     hidden_dynamic_lds_size
    .group_segment_fixed_size: 0
    .kernarg_segment_align: 8
    .kernarg_segment_size: 408
    .language:       OpenCL C
    .language_version:
      - 2
      - 0
    .max_flat_workgroup_size: 512
    .name:           _Z14fwd_megakernel4Args
    .private_segment_fixed_size: 0
    .sgpr_count:     108
    .sgpr_spill_count: 88
    .symbol:         _Z14fwd_megakernel4Args.kd
    .uniform_work_group_size: 1
    .uses_dynamic_stack: false
    .vgpr_count:     255
    .vgpr_spill_count: 0
    .wavefront_size: 64
